# P2 mixer loop: top-of-unit drain relaxed to vmcnt(12) so the previous unit's stores stay in flight (full drain kept on the entry edge)
# speedup vs baseline: 1.0083x; 1.0057x over previous
.LBB0_311:
	s_or_b64 exec, exec, s[0:1]
	v_readlane_b32 s36, v249, 0
	v_readlane_b32 s48, v249, 12
	v_readlane_b32 s49, v249, 13
	v_readlane_b32 s50, v249, 14
	v_readlane_b32 s51, v249, 15
	s_mov_b64 s[28:29], s[48:49]
	s_mov_b64 s[30:31], s[50:51]
	v_lshlrev_b32_e32 v226, 1, v222
	v_readlane_b32 s37, v249, 1
	s_add_u32 s24, s30, 0xea00000
	v_or_b32_e32 v9, s3, v226
	s_movk_i32 s10, 0x1c00
	v_mov_b64_e32 v[10:11], s[20:21]
	s_addc_u32 s25, s31, 0
	v_mad_i64_i32 v[10:11], s[0:1], v9, s10, v[10:11]
	s_lshl_b32 s36, s75, 4
	s_mov_b32 s37, s23
	v_lshl_add_u64 v[10:11], v[10:11], 0, s[36:37]
	v_lshl_add_u64 v[10:11], v[10:11], 0, s[22:23]
	s_movk_i32 s0, 0x2000
	v_add_co_u32_e64 v44, s[0:1], s0, v10
	v_lshlrev_b32_e32 v9, 4, v219
	s_nop 0
	v_addc_co_u32_e64 v45, s[0:1], 0, v11, s[0:1]
	global_load_dwordx4 v[28:31], v[44:45], off offset:1152
	global_load_dwordx4 v[32:35], v[44:45], off offset:1024
	global_load_dwordx4 v[36:39], v[10:11], off offset:2176
	global_load_dwordx4 v[24:27], v[10:11], off offset:2048
	v_and_b32_e32 v10, 0xf0, v9
	v_add_u32_e32 v11, 0, v10
	v_lshrrev_b32_e32 v10, 1, v219
	v_and_b32_e32 v10, 24, v10
	v_readlane_b32 s0, v249, 48
	v_lshlrev_b32_e32 v44, 1, v10
	v_mov_b32_e32 v45, v8
	s_lshr_b32 s11, s0, 8
	v_lshl_add_u64 v[44:45], s[30:31], 0, v[44:45]
	s_mov_b64 s[0:1], 0x1f00000
	s_lshl_b32 s14, s75, 5
	v_lshl_add_u64 v[192:193], v[44:45], 0, s[0:1]
	s_mov_b64 s[0:1], 0x1f40000
	v_readlane_b32 s38, v249, 2
	s_add_i32 s3, 0, 0x11800
	s_and_b32 s15, s14, 0x60
	v_and_b32_e32 v47, 24, v226
	v_and_b32_e32 v48, 3, v219
	s_or_b32 s33, s36, 8
	v_lshl_add_u64 v[196:197], v[44:45], 0, s[0:1]
	s_lshl_b32 s0, s11, 6
	v_readlane_b32 s39, v249, 3
	v_mov_b32_e32 v41, v8
	v_or3_b32 v44, s0, v48, v47
	s_movk_i32 s1, 0x110
	s_add_u32 s38, s20, s36
	v_lshl_add_u64 v[194:195], s[20:21], 0, v[40:41]
	v_add_u32_e32 v40, 0x600, v219
	v_mul_lo_u32 v44, v44, s1
	s_addc_u32 s39, s21, 0
	s_lshl_b32 s1, s75, 12
	v_and_b32_e32 v227, 15, v219
	v_lshlrev_b32_e32 v228, 2, v222
	v_or3_b32 v229, v47, v48, s14
	v_lshrrev_b32_e32 v232, 4, v40
	v_and_b32_e32 v41, 48, v219
	v_lshlrev_b32_e32 v42, 4, v42
	v_lshlrev_b32_e32 v40, 4, v40
	v_lshlrev_b32_e32 v43, 4, v43
	v_or_b32_e32 v47, 48, v222
	v_or_b32_e32 v48, 0x70, v222
	s_add_i32 s34, s1, 0
	s_mul_i32 s1, s75, 0x1100
	v_readlane_b32 s42, v249, 6
	v_readlane_b32 s43, v249, 7
	v_add_u32_e32 v46, s3, v228
	v_add_u32_e32 v49, 0, v41
	v_or_b32_e32 v233, s15, v227
	v_add_u32_e32 v41, s3, v41
	v_and_b32_e32 v9, 0x3f00, v9
	v_and_b32_e32 v42, 0x7f00, v42
	v_and_b32_e32 v40, 0xff00, v40
	v_and_b32_e32 v43, 0xbf00, v43
	s_mul_i32 s0, s75, 0x880
	v_mul_u32_u24_e32 v45, 0x110, v227
	v_mul_u32_u24_e32 v47, 0x110, v47
	v_mul_u32_u24_e32 v48, 0x110, v48
	s_addk_i32 s34, 0x800
	s_add_i32 s37, s1, 0
	v_or_b32_e32 v230, s14, v10
	v_or_b32_e32 v231, 64, v223
	v_or_b32_e32 v234, 16, v233
	v_add_u32_e32 v235, s34, v228
	s_sub_i32 s35, 0, s36
	s_add_i32 s37, s37, 0x9000
	v_add_u32_e32 v236, v11, v9
	v_add_u32_e32 v237, v11, v42
	v_add_u32_e32 v238, v11, v40
	v_add_u32_e32 v239, v11, v43
	v_add_u32_e32 v240, s0, v46
	s_mov_b32 s48, 0xffff0000
	s_movk_i32 s49, 0xfff
	s_xor_b64 s[42:43], vcc, -1
	v_add_u32_e32 v241, v49, v45
	v_add_u32_e32 v242, v49, v47
	v_add_u32_e32 v243, v49, v48
	s_movk_i32 s52, 0x1000
	v_lshlrev_b32_e32 v198, 1, v10
	v_add_u32_e32 v244, v41, v44
	s_mov_b32 s53, s2
	v_readlane_b32 s40, v249, 4
	v_readlane_b32 s41, v249, 5
	v_readlane_b32 s44, v249, 8
	v_readlane_b32 s45, v249, 9
	v_readlane_b32 s46, v249, 10
	v_readlane_b32 s47, v249, 11
	s_waitcnt vmcnt(0)
	s_branch .LBB0_314

.LBB0_314:
	s_waitcnt vmcnt(12)
	ds_write_b128 v236, v[4:7]
	ds_write_b128 v237, v[12:15]
	ds_write_b128 v236, v[16:19] offset:16384
	s_and_saveexec_b64 s[0:1], s[12:13]
	ds_write_b128 v238, v[0:3]
	s_or_b64 exec, exec, s[0:1]
	s_and_saveexec_b64 s[0:1], s[6:7]
	ds_write_b128 v239, v[20:23]
	s_or_b64 exec, exec, s[0:1]
	s_lshl_b32 s0, s53, 5
	s_and_b32 s40, s53, 3
	s_and_b32 s3, s0, 0xffffff80
	s_lshl_b32 s0, s40, 8
	v_add_u32_e32 v10, s0, v229
	v_ashrrev_i32_e32 v11, 31, v10
	v_lshlrev_b64 v[40:41], 8, v[10:11]
	v_or_b32_e32 v10, 4, v10
	v_ashrrev_i32_e32 v11, 31, v10
	v_lshlrev_b64 v[10:11], 8, v[10:11]
	v_lshl_add_u64 v[40:41], v[192:193], 0, v[40:41]
	v_lshl_add_u64 v[10:11], v[192:193], 0, v[10:11]
	v_add_u32_e32 v220, s0, v230
	global_load_dwordx4 v[84:87], v[40:41], off
	global_load_dwordx4 v[80:83], v[40:41], off offset:64
	global_load_dwordx4 v[76:79], v[40:41], off offset:128
	global_load_dwordx4 v[72:75], v[40:41], off offset:192
	global_load_dwordx4 v[100:103], v[10:11], off
	global_load_dwordx4 v[96:99], v[10:11], off offset:64
	global_load_dwordx4 v[92:95], v[10:11], off offset:128
	global_load_dwordx4 v[88:91], v[10:11], off offset:192
	v_or_b32_e32 v214, s3, v227
	v_ashrrev_i32_e32 v221, 31, v220
	v_mov_b64_e32 v[10:11], s[20:21]
	v_mad_i64_i32 v[40:41], s[0:1], v214, s10, v[10:11]
	v_lshlrev_b64 v[42:43], 1, v[220:221]
	v_or_b32_e32 v212, 16, v214
	v_lshl_add_u64 v[40:41], v[40:41], 0, v[42:43]
	v_mad_i64_i32 v[44:45], s[0:1], v212, s10, v[10:11]
	v_or_b32_e32 v210, 32, v214
	v_lshl_add_u64 v[44:45], v[44:45], 0, v[42:43]
	global_load_dwordx4 v[68:71], v[40:41], off offset:3072
	global_load_dwordx4 v[64:67], v[44:45], off offset:3072
	v_mad_i64_i32 v[40:41], s[0:1], v210, s10, v[10:11]
	v_or_b32_e32 v208, 48, v214
	v_lshl_add_u64 v[40:41], v[40:41], 0, v[42:43]
	v_mad_i64_i32 v[44:45], s[0:1], v208, s10, v[10:11]
	v_or_b32_e32 v206, 64, v214
	v_lshl_add_u64 v[44:45], v[44:45], 0, v[42:43]
	global_load_dwordx4 v[60:63], v[40:41], off offset:3072
	global_load_dwordx4 v[56:59], v[44:45], off offset:3072
	v_mad_i64_i32 v[40:41], s[0:1], v206, s10, v[10:11]
	v_or_b32_e32 v204, 0x50, v214
	v_lshl_add_u64 v[40:41], v[40:41], 0, v[42:43]
	v_mad_i64_i32 v[44:45], s[0:1], v204, s10, v[10:11]
	v_or_b32_e32 v202, 0x60, v214
	v_lshl_add_u64 v[44:45], v[44:45], 0, v[42:43]
	global_load_dwordx4 v[52:55], v[40:41], off offset:3072
	global_load_dwordx4 v[48:51], v[44:45], off offset:3072
	v_mad_i64_i32 v[40:41], s[0:1], v202, s10, v[10:11]
	v_or_b32_e32 v200, 0x70, v214
	v_lshl_add_u64 v[40:41], v[40:41], 0, v[42:43]
	v_mad_i64_i32 v[10:11], s[0:1], v200, s10, v[10:11]
	v_lshl_add_u64 v[10:11], v[10:11], 0, v[42:43]
	global_load_dwordx4 v[44:47], v[40:41], off offset:3072
	s_nop 0
	global_load_dwordx4 v[40:43], v[10:11], off offset:3072
	v_and_b32_e32 v9, 0xffff, v24
	v_lshrrev_b32_e32 v10, 16, v24
	v_lshl_or_b32 v9, v32, 16, v9
	v_and_or_b32 v10, v32, s48, v10
	ds_write2_b32 v240, v9, v10 offset1:68
	v_and_b32_e32 v9, 0xffff, v25
	v_lshrrev_b32_e32 v10, 16, v25
	v_lshl_or_b32 v9, v33, 16, v9
	v_and_or_b32 v10, v33, s48, v10
	ds_write2_b32 v240, v9, v10 offset0:136 offset1:204
	v_and_b32_e32 v9, 0xffff, v26
	v_lshrrev_b32_e32 v10, 16, v26
	v_lshl_or_b32 v9, v34, 16, v9
	v_and_or_b32 v10, v34, s48, v10
	v_add_u32_e32 v11, 0x400, v240
	ds_write2_b32 v11, v9, v10 offset0:16 offset1:84
	v_and_b32_e32 v9, 0xffff, v27
	v_lshrrev_b32_e32 v10, 16, v27
	v_lshl_or_b32 v9, v35, 16, v9
	v_and_or_b32 v10, v35, s48, v10
	ds_write2_b32 v11, v9, v10 offset0:152 offset1:220
	v_and_b32_e32 v9, 0xffff, v36
	v_lshrrev_b32_e32 v10, 16, v36
	v_lshl_or_b32 v9, v28, 16, v9
	v_and_or_b32 v10, v28, s48, v10
	v_add_u32_e32 v11, 0x4400, v240
	ds_write2_b32 v11, v9, v10 offset1:68
	v_and_b32_e32 v9, 0xffff, v37
	v_lshrrev_b32_e32 v10, 16, v37
	v_lshl_or_b32 v9, v29, 16, v9
	v_and_or_b32 v10, v29, s48, v10
	ds_write2_b32 v11, v9, v10 offset0:136 offset1:204
	v_and_b32_e32 v9, 0xffff, v38
	v_lshrrev_b32_e32 v10, 16, v38
	v_lshl_or_b32 v9, v30, 16, v9
	v_and_or_b32 v10, v30, s48, v10
	v_add_u32_e32 v11, 0x4800, v240
	ds_write2_b32 v11, v9, v10 offset0:16 offset1:84
	v_and_b32_e32 v9, 0xffff, v39
	v_lshrrev_b32_e32 v10, 16, v39
	v_lshl_or_b32 v9, v31, 16, v9
	v_and_or_b32 v10, v31, s48, v10
	s_lshl_b32 s22, 1, s40
	ds_write2_b32 v11, v9, v10 offset0:152 offset1:220
	s_lshl_b32 s0, s22, 8
	v_mov_b32_e32 v10, 0
	v_ashrrev_i32_e32 v215, 31, v214
	v_ashrrev_i32_e32 v213, 31, v212
	v_ashrrev_i32_e32 v211, 31, v210
	v_ashrrev_i32_e32 v209, 31, v208
	v_ashrrev_i32_e32 v207, 31, v206
	v_ashrrev_i32_e32 v205, 31, v204
	v_ashrrev_i32_e32 v203, 31, v202
	v_ashrrev_i32_e32 v201, 31, v200
	s_add_i32 s14, s22, s33
	s_sub_i32 s15, s33, s22
	s_sub_i32 s1, 0, s0
	v_subrev_u32_e32 v9, s0, v235
	v_mov_b32_e32 v11, v10
	s_waitcnt lgkmcnt(0)
	s_barrier
